# P0 FFN weight transposes: the 32 row loads of the next item issued together (one wait) instead of 16 serialized load-wait-copy steps
# speedup vs baseline: 1.0029x; 1.0020x over previous
; template <class Map>
; DI void p0_transpose(const float* W, int K, int N, bf16_t* WT, const float* gain, const Map map, LAS float* scr, int& base, int gw, int NGW, int lane) {
;     ...
;     auto loadit = [&](int it, float (&dst)[32]) {
;         const int kb = it / nblk, nb = it % nblk, k0 = 64 * kb, c = 32 * nb + (lane & 31);
;         const float* p = W + (size_t)(k0 + (lane >> 5)) * N + c;
; #pragma unroll
;         for (int i = 0; i < 32; ++i) dst[i] = (c < N) ? p[(size_t)(2 * i) * N] : 0.f;
;     };
;     if (first < nitems) loadit(first, cur);
;     for (int it = first; it < nitems; it += NGW) {
;         const bool more = it + NGW < nitems;
;         if (more) loadit(it + NGW, nxt);
.LBB0_48:
	s_or_saveexec_b64 s[92:93], s[92:93]
	v_lshl_or_b32 v3, s54, 6, v100
	v_mov_b64_e32 v[38:39], s[82:83]
	v_mad_i64_i32 v[38:39], s[54:55], v3, s39, v[38:39]
	v_ashrrev_i32_e32 v37, 31, v36
	v_lshl_add_u64 v[122:123], v[36:37], 2, v[38:39]
	s_mov_b32 s94, 0x5800
	s_mov_b32 s95, 0
	v_mov_b32_e32 v236, v122
	v_mov_b32_e32 v237, v123
	global_load_dword v204, v[236:237], off
	v_lshl_add_u64 v[236:237], v[236:237], 0, s[94:95]
	global_load_dword v205, v[236:237], off
	v_lshl_add_u64 v[236:237], v[236:237], 0, s[94:95]
	global_load_dword v206, v[236:237], off
	v_lshl_add_u64 v[236:237], v[236:237], 0, s[94:95]
	global_load_dword v207, v[236:237], off
	v_lshl_add_u64 v[236:237], v[236:237], 0, s[94:95]
	global_load_dword v208, v[236:237], off
	v_lshl_add_u64 v[236:237], v[236:237], 0, s[94:95]
	global_load_dword v209, v[236:237], off
	v_lshl_add_u64 v[236:237], v[236:237], 0, s[94:95]
	global_load_dword v210, v[236:237], off
	v_lshl_add_u64 v[236:237], v[236:237], 0, s[94:95]
	global_load_dword v211, v[236:237], off
	v_lshl_add_u64 v[236:237], v[236:237], 0, s[94:95]
	global_load_dword v212, v[236:237], off
	v_lshl_add_u64 v[236:237], v[236:237], 0, s[94:95]
	global_load_dword v213, v[236:237], off
	v_lshl_add_u64 v[236:237], v[236:237], 0, s[94:95]
	global_load_dword v214, v[236:237], off
	v_lshl_add_u64 v[236:237], v[236:237], 0, s[94:95]
	global_load_dword v215, v[236:237], off
	v_lshl_add_u64 v[236:237], v[236:237], 0, s[94:95]
	global_load_dword v216, v[236:237], off
	v_lshl_add_u64 v[236:237], v[236:237], 0, s[94:95]
	global_load_dword v217, v[236:237], off
	v_lshl_add_u64 v[236:237], v[236:237], 0, s[94:95]
	global_load_dword v218, v[236:237], off
	v_lshl_add_u64 v[236:237], v[236:237], 0, s[94:95]
	global_load_dword v219, v[236:237], off
	v_lshl_add_u64 v[236:237], v[236:237], 0, s[94:95]
	global_load_dword v220, v[236:237], off
	v_lshl_add_u64 v[236:237], v[236:237], 0, s[94:95]
	global_load_dword v221, v[236:237], off
	v_lshl_add_u64 v[236:237], v[236:237], 0, s[94:95]
	global_load_dword v222, v[236:237], off
	v_lshl_add_u64 v[236:237], v[236:237], 0, s[94:95]
	global_load_dword v223, v[236:237], off
	v_lshl_add_u64 v[236:237], v[236:237], 0, s[94:95]
	global_load_dword v224, v[236:237], off
	v_lshl_add_u64 v[236:237], v[236:237], 0, s[94:95]
	global_load_dword v225, v[236:237], off
	v_lshl_add_u64 v[236:237], v[236:237], 0, s[94:95]
	global_load_dword v226, v[236:237], off
	v_lshl_add_u64 v[236:237], v[236:237], 0, s[94:95]
	global_load_dword v227, v[236:237], off
	v_lshl_add_u64 v[236:237], v[236:237], 0, s[94:95]
	global_load_dword v228, v[236:237], off
	v_lshl_add_u64 v[236:237], v[236:237], 0, s[94:95]
	global_load_dword v229, v[236:237], off
	v_lshl_add_u64 v[236:237], v[236:237], 0, s[94:95]
	global_load_dword v230, v[236:237], off
	v_lshl_add_u64 v[236:237], v[236:237], 0, s[94:95]
	global_load_dword v231, v[236:237], off
	v_lshl_add_u64 v[236:237], v[236:237], 0, s[94:95]
	global_load_dword v232, v[236:237], off
	v_lshl_add_u64 v[236:237], v[236:237], 0, s[94:95]
	global_load_dword v233, v[236:237], off
	v_lshl_add_u64 v[236:237], v[236:237], 0, s[94:95]
	global_load_dword v234, v[236:237], off
	v_lshl_add_u64 v[236:237], v[236:237], 0, s[94:95]
	global_load_dword v235, v[236:237], off
	s_waitcnt vmcnt(0)
	s_waitcnt vmcnt(4)
	v_mov_b32_e32 v5, 0
	s_xor_b64 exec, exec, s[92:93]
	s_cbranch_execz .LBB0_50
	v_add_co_u32_e32 v6, vcc, 0x5000, v122
	s_nop 1
	v_addc_co_u32_e32 v7, vcc, 0, v123, vcc
	v_mov_b32_e32 v4, v204
	v_mov_b32_e32 v5, v205

; template <class Map>
; DI void p0_transpose(const float* W, int K, int N, bf16_t* WT, const float* gain, const Map map, LAS float* scr, int& base, int gw, int NGW, int lane) {
;     ...
;         const int kb = it / nblk, nb = it % nblk, k0 = 64 * kb, c = 32 * nb + (lane & 31);
;         const float* p = W + (size_t)(k0 + (lane >> 5)) * N + c;
; #pragma unroll
;         for (int i = 0; i < 32; ++i) dst[i] = (c < N) ? p[(size_t)(2 * i) * N] : 0.f;
.LBB0_53:
	v_add_co_u32_e32 v36, vcc, 0xb000, v122
	s_nop 1
	v_addc_co_u32_e32 v37, vcc, 0, v123, vcc
	v_add_co_u32_e32 v38, vcc, 0x10000, v122
	s_nop 1
	v_addc_co_u32_e32 v39, vcc, 0, v123, vcc
	v_mov_b32_e32 v6, v206
	v_mov_b32_e32 v3, v207
	s_waitcnt vmcnt(1)
	v_mov_b64_e32 v[66:67], v[34:35]
	v_mov_b64_e32 v[38:39], v[6:7]
	v_mov_b64_e32 v[64:65], v[32:33]
	v_mov_b64_e32 v[62:63], v[30:31]
	v_mov_b64_e32 v[60:61], v[28:29]
	v_mov_b64_e32 v[58:59], v[26:27]
	v_mov_b64_e32 v[56:57], v[24:25]
	v_mov_b64_e32 v[54:55], v[22:23]
	v_mov_b64_e32 v[52:53], v[20:21]
	v_mov_b64_e32 v[50:51], v[18:19]
	v_mov_b64_e32 v[48:49], v[16:17]
	v_mov_b64_e32 v[46:47], v[14:15]
	v_mov_b64_e32 v[44:45], v[12:13]
	v_mov_b64_e32 v[42:43], v[10:11]
	v_mov_b64_e32 v[40:41], v[8:9]
	v_mov_b64_e32 v[36:37], v[4:5]
	s_waitcnt vmcnt(0)
	v_mov_b32_e32 v39, v3

; template <class Map>
; DI void p0_transpose(const float* W, int K, int N, bf16_t* WT, const float* gain, const Map map, LAS float* scr, int& base, int gw, int NGW, int lane) {
;     ...
;         const int kb = it / nblk, nb = it % nblk, k0 = 64 * kb, c = 32 * nb + (lane & 31);
;         const float* p = W + (size_t)(k0 + (lane >> 5)) * N + c;
; #pragma unroll
;         for (int i = 0; i < 32; ++i) dst[i] = (c < N) ? p[(size_t)(2 * i) * N] : 0.f;
.LBB0_57:
	s_waitcnt vmcnt(1)
	v_add_co_u32_e32 v4, vcc, 0x16000, v122
	s_waitcnt vmcnt(0)
	s_nop 0
	v_addc_co_u32_e32 v5, vcc, 0, v123, vcc
	v_add_co_u32_e32 v6, vcc, 0x1b000, v122
	s_nop 1
	v_addc_co_u32_e32 v7, vcc, 0, v123, vcc
	v_mov_b32_e32 v40, v208
	v_mov_b32_e32 v3, v209
	s_waitcnt vmcnt(1)
	v_mov_b64_e32 v[4:5], v[36:37]
	v_mov_b64_e32 v[8:9], v[40:41]
	v_mov_b64_e32 v[6:7], v[38:39]
	v_mov_b64_e32 v[10:11], v[42:43]
	v_mov_b64_e32 v[12:13], v[44:45]
	v_mov_b64_e32 v[14:15], v[46:47]
	v_mov_b64_e32 v[16:17], v[48:49]
	v_mov_b64_e32 v[18:19], v[50:51]
	v_mov_b64_e32 v[20:21], v[52:53]
	v_mov_b64_e32 v[22:23], v[54:55]
	v_mov_b64_e32 v[24:25], v[56:57]
	v_mov_b64_e32 v[26:27], v[58:59]
	v_mov_b64_e32 v[28:29], v[60:61]
	v_mov_b64_e32 v[30:31], v[62:63]
	v_mov_b64_e32 v[32:33], v[64:65]
	v_mov_b64_e32 v[34:35], v[66:67]
	s_waitcnt vmcnt(0)
	v_mov_b32_e32 v9, v3

; template <class Map>
; DI void p0_transpose(const float* W, int K, int N, bf16_t* WT, const float* gain, const Map map, LAS float* scr, int& base, int gw, int NGW, int lane) {
;     ...
;         const int kb = it / nblk, nb = it % nblk, k0 = 64 * kb, c = 32 * nb + (lane & 31);
;         const float* p = W + (size_t)(k0 + (lane >> 5)) * N + c;
; #pragma unroll
;         for (int i = 0; i < 32; ++i) dst[i] = (c < N) ? p[(size_t)(2 * i) * N] : 0.f;
.LBB0_61:
	v_add_co_u32_e32 v36, vcc, 0x21000, v122
	s_nop 1
	v_addc_co_u32_e32 v37, vcc, 0, v123, vcc
	v_add_co_u32_e32 v38, vcc, 0x26000, v122
	s_nop 1
	v_addc_co_u32_e32 v39, vcc, 0, v123, vcc
	v_mov_b32_e32 v10, v210
	v_mov_b32_e32 v3, v211
	s_waitcnt vmcnt(1)
	v_mov_b64_e32 v[66:67], v[34:35]
	v_mov_b64_e32 v[42:43], v[10:11]
	v_mov_b64_e32 v[64:65], v[32:33]
	v_mov_b64_e32 v[62:63], v[30:31]
	v_mov_b64_e32 v[60:61], v[28:29]
	v_mov_b64_e32 v[58:59], v[26:27]
	v_mov_b64_e32 v[56:57], v[24:25]
	v_mov_b64_e32 v[54:55], v[22:23]
	v_mov_b64_e32 v[52:53], v[20:21]
	v_mov_b64_e32 v[50:51], v[18:19]
	v_mov_b64_e32 v[48:49], v[16:17]
	v_mov_b64_e32 v[46:47], v[14:15]
	v_mov_b64_e32 v[44:45], v[12:13]
	v_mov_b64_e32 v[40:41], v[8:9]
	v_mov_b64_e32 v[38:39], v[6:7]
	v_mov_b64_e32 v[36:37], v[4:5]
	s_waitcnt vmcnt(0)
	v_mov_b32_e32 v43, v3

; template <class Map>
; DI void p0_transpose(const float* W, int K, int N, bf16_t* WT, const float* gain, const Map map, LAS float* scr, int& base, int gw, int NGW, int lane) {
;     ...
;         const int kb = it / nblk, nb = it % nblk, k0 = 64 * kb, c = 32 * nb + (lane & 31);
;         const float* p = W + (size_t)(k0 + (lane >> 5)) * N + c;
; #pragma unroll
;         for (int i = 0; i < 32; ++i) dst[i] = (c < N) ? p[(size_t)(2 * i) * N] : 0.f;
.LBB0_65:
	s_waitcnt vmcnt(1)
	v_add_co_u32_e32 v4, vcc, 0x2c000, v122
	s_waitcnt vmcnt(0)
	s_nop 0
	v_addc_co_u32_e32 v5, vcc, 0, v123, vcc
	v_add_co_u32_e32 v6, vcc, 0x31000, v122
	s_nop 1
	v_addc_co_u32_e32 v7, vcc, 0, v123, vcc
	v_mov_b32_e32 v44, v212
	v_mov_b32_e32 v3, v213
	s_waitcnt vmcnt(1)
	v_mov_b64_e32 v[4:5], v[36:37]
	v_mov_b64_e32 v[12:13], v[44:45]
	v_mov_b64_e32 v[6:7], v[38:39]
	v_mov_b64_e32 v[8:9], v[40:41]
	v_mov_b64_e32 v[10:11], v[42:43]
	v_mov_b64_e32 v[14:15], v[46:47]
	v_mov_b64_e32 v[16:17], v[48:49]
	v_mov_b64_e32 v[18:19], v[50:51]
	v_mov_b64_e32 v[20:21], v[52:53]
	v_mov_b64_e32 v[22:23], v[54:55]
	v_mov_b64_e32 v[24:25], v[56:57]
	v_mov_b64_e32 v[26:27], v[58:59]
	v_mov_b64_e32 v[28:29], v[60:61]
	v_mov_b64_e32 v[30:31], v[62:63]
	v_mov_b64_e32 v[32:33], v[64:65]
	v_mov_b64_e32 v[34:35], v[66:67]
	s_waitcnt vmcnt(0)
	v_mov_b32_e32 v13, v3

; template <class Map>
; DI void p0_transpose(const float* W, int K, int N, bf16_t* WT, const float* gain, const Map map, LAS float* scr, int& base, int gw, int NGW, int lane) {
;     ...
;         const int kb = it / nblk, nb = it % nblk, k0 = 64 * kb, c = 32 * nb + (lane & 31);
;         const float* p = W + (size_t)(k0 + (lane >> 5)) * N + c;
; #pragma unroll
;         for (int i = 0; i < 32; ++i) dst[i] = (c < N) ? p[(size_t)(2 * i) * N] : 0.f;
.LBB0_69:
	v_add_co_u32_e32 v36, vcc, 0x37000, v122
	s_nop 1
	v_addc_co_u32_e32 v37, vcc, 0, v123, vcc
	v_add_co_u32_e32 v38, vcc, 0x3c000, v122
	s_nop 1
	v_addc_co_u32_e32 v39, vcc, 0, v123, vcc
	v_mov_b32_e32 v14, v214
	v_mov_b32_e32 v3, v215
	s_waitcnt vmcnt(1)
	v_mov_b64_e32 v[66:67], v[34:35]
	v_mov_b64_e32 v[46:47], v[14:15]
	v_mov_b64_e32 v[64:65], v[32:33]
	v_mov_b64_e32 v[62:63], v[30:31]
	v_mov_b64_e32 v[60:61], v[28:29]
	v_mov_b64_e32 v[58:59], v[26:27]
	v_mov_b64_e32 v[56:57], v[24:25]
	v_mov_b64_e32 v[54:55], v[22:23]
	v_mov_b64_e32 v[52:53], v[20:21]
	v_mov_b64_e32 v[50:51], v[18:19]
	v_mov_b64_e32 v[48:49], v[16:17]
	v_mov_b64_e32 v[44:45], v[12:13]
	v_mov_b64_e32 v[42:43], v[10:11]
	v_mov_b64_e32 v[40:41], v[8:9]
	v_mov_b64_e32 v[38:39], v[6:7]
	v_mov_b64_e32 v[36:37], v[4:5]
	s_waitcnt vmcnt(0)
	v_mov_b32_e32 v47, v3

; template <class Map>
; DI void p0_transpose(const float* W, int K, int N, bf16_t* WT, const float* gain, const Map map, LAS float* scr, int& base, int gw, int NGW, int lane) {
;     ...
;         const int kb = it / nblk, nb = it % nblk, k0 = 64 * kb, c = 32 * nb + (lane & 31);
;         const float* p = W + (size_t)(k0 + (lane >> 5)) * N + c;
; #pragma unroll
;         for (int i = 0; i < 32; ++i) dst[i] = (c < N) ? p[(size_t)(2 * i) * N] : 0.f;
.LBB0_73:
	s_waitcnt vmcnt(1)
	v_add_co_u32_e32 v4, vcc, 0x42000, v122
	s_waitcnt vmcnt(0)
	s_nop 0
	v_addc_co_u32_e32 v5, vcc, 0, v123, vcc
	v_add_co_u32_e32 v6, vcc, 0x47000, v122
	s_nop 1
	v_addc_co_u32_e32 v7, vcc, 0, v123, vcc
	v_mov_b32_e32 v48, v216
	v_mov_b32_e32 v3, v217
	s_waitcnt vmcnt(1)
	v_mov_b64_e32 v[4:5], v[36:37]
	v_mov_b64_e32 v[16:17], v[48:49]
	v_mov_b64_e32 v[6:7], v[38:39]
	v_mov_b64_e32 v[8:9], v[40:41]
	v_mov_b64_e32 v[10:11], v[42:43]
	v_mov_b64_e32 v[12:13], v[44:45]
	v_mov_b64_e32 v[14:15], v[46:47]
	v_mov_b64_e32 v[18:19], v[50:51]
	v_mov_b64_e32 v[20:21], v[52:53]
	v_mov_b64_e32 v[22:23], v[54:55]
	v_mov_b64_e32 v[24:25], v[56:57]
	v_mov_b64_e32 v[26:27], v[58:59]
	v_mov_b64_e32 v[28:29], v[60:61]
	v_mov_b64_e32 v[30:31], v[62:63]
	v_mov_b64_e32 v[32:33], v[64:65]
	v_mov_b64_e32 v[34:35], v[66:67]
	s_waitcnt vmcnt(0)
	v_mov_b32_e32 v17, v3

; template <class Map>
; DI void p0_transpose(const float* W, int K, int N, bf16_t* WT, const float* gain, const Map map, LAS float* scr, int& base, int gw, int NGW, int lane) {
;     ...
;         const int kb = it / nblk, nb = it % nblk, k0 = 64 * kb, c = 32 * nb + (lane & 31);
;         const float* p = W + (size_t)(k0 + (lane >> 5)) * N + c;
; #pragma unroll
;         for (int i = 0; i < 32; ++i) dst[i] = (c < N) ? p[(size_t)(2 * i) * N] : 0.f;
.LBB0_77:
	v_add_co_u32_e32 v36, vcc, 0x4d000, v122
	s_nop 1
	v_addc_co_u32_e32 v37, vcc, 0, v123, vcc
	v_add_co_u32_e32 v38, vcc, 0x52000, v122
	s_nop 1
	v_addc_co_u32_e32 v39, vcc, 0, v123, vcc
	v_mov_b32_e32 v18, v218
	v_mov_b32_e32 v3, v219
	s_waitcnt vmcnt(1)
	v_mov_b64_e32 v[66:67], v[34:35]
	v_mov_b64_e32 v[50:51], v[18:19]
	v_mov_b64_e32 v[64:65], v[32:33]
	v_mov_b64_e32 v[62:63], v[30:31]
	v_mov_b64_e32 v[60:61], v[28:29]
	v_mov_b64_e32 v[58:59], v[26:27]
	v_mov_b64_e32 v[56:57], v[24:25]
	v_mov_b64_e32 v[54:55], v[22:23]
	v_mov_b64_e32 v[52:53], v[20:21]
	v_mov_b64_e32 v[48:49], v[16:17]
	v_mov_b64_e32 v[46:47], v[14:15]
	v_mov_b64_e32 v[44:45], v[12:13]
	v_mov_b64_e32 v[42:43], v[10:11]
	v_mov_b64_e32 v[40:41], v[8:9]
	v_mov_b64_e32 v[38:39], v[6:7]
	v_mov_b64_e32 v[36:37], v[4:5]
	s_waitcnt vmcnt(0)
	v_mov_b32_e32 v51, v3

; template <class Map>
; DI void p0_transpose(const float* W, int K, int N, bf16_t* WT, const float* gain, const Map map, LAS float* scr, int& base, int gw, int NGW, int lane) {
;     ...
;         const int kb = it / nblk, nb = it % nblk, k0 = 64 * kb, c = 32 * nb + (lane & 31);
;         const float* p = W + (size_t)(k0 + (lane >> 5)) * N + c;
; #pragma unroll
;         for (int i = 0; i < 32; ++i) dst[i] = (c < N) ? p[(size_t)(2 * i) * N] : 0.f;
.LBB0_81:
	s_waitcnt vmcnt(1)
	v_add_co_u32_e32 v4, vcc, 0x58000, v122
	s_waitcnt vmcnt(0)
	s_nop 0
	v_addc_co_u32_e32 v5, vcc, 0, v123, vcc
	v_add_co_u32_e32 v6, vcc, 0x5d000, v122
	s_nop 1
	v_addc_co_u32_e32 v7, vcc, 0, v123, vcc
	v_mov_b32_e32 v52, v220
	v_mov_b32_e32 v3, v221
	s_waitcnt vmcnt(1)
	v_mov_b64_e32 v[4:5], v[36:37]
	v_mov_b64_e32 v[20:21], v[52:53]
	v_mov_b64_e32 v[6:7], v[38:39]
	v_mov_b64_e32 v[8:9], v[40:41]
	v_mov_b64_e32 v[10:11], v[42:43]
	v_mov_b64_e32 v[12:13], v[44:45]
	v_mov_b64_e32 v[14:15], v[46:47]
	v_mov_b64_e32 v[16:17], v[48:49]
	v_mov_b64_e32 v[18:19], v[50:51]
	v_mov_b64_e32 v[22:23], v[54:55]
	v_mov_b64_e32 v[24:25], v[56:57]
	v_mov_b64_e32 v[26:27], v[58:59]
	v_mov_b64_e32 v[28:29], v[60:61]
	v_mov_b64_e32 v[30:31], v[62:63]
	v_mov_b64_e32 v[32:33], v[64:65]
	v_mov_b64_e32 v[34:35], v[66:67]
	s_waitcnt vmcnt(0)
	v_mov_b32_e32 v21, v3

; template <class Map>
; DI void p0_transpose(const float* W, int K, int N, bf16_t* WT, const float* gain, const Map map, LAS float* scr, int& base, int gw, int NGW, int lane) {
;     ...
;         const int kb = it / nblk, nb = it % nblk, k0 = 64 * kb, c = 32 * nb + (lane & 31);
;         const float* p = W + (size_t)(k0 + (lane >> 5)) * N + c;
; #pragma unroll
;         for (int i = 0; i < 32; ++i) dst[i] = (c < N) ? p[(size_t)(2 * i) * N] : 0.f;
.LBB0_85:
	v_add_co_u32_e32 v36, vcc, 0x63000, v122
	s_nop 1
	v_addc_co_u32_e32 v37, vcc, 0, v123, vcc
	v_add_co_u32_e32 v38, vcc, 0x68000, v122
	s_nop 1
	v_addc_co_u32_e32 v39, vcc, 0, v123, vcc
	v_mov_b32_e32 v22, v222
	v_mov_b32_e32 v3, v223
	s_waitcnt vmcnt(1)
	v_mov_b64_e32 v[66:67], v[34:35]
	v_mov_b64_e32 v[54:55], v[22:23]
	v_mov_b64_e32 v[64:65], v[32:33]
	v_mov_b64_e32 v[62:63], v[30:31]
	v_mov_b64_e32 v[60:61], v[28:29]
	v_mov_b64_e32 v[58:59], v[26:27]
	v_mov_b64_e32 v[56:57], v[24:25]
	v_mov_b64_e32 v[52:53], v[20:21]
	v_mov_b64_e32 v[50:51], v[18:19]
	v_mov_b64_e32 v[48:49], v[16:17]
	v_mov_b64_e32 v[46:47], v[14:15]
	v_mov_b64_e32 v[44:45], v[12:13]
	v_mov_b64_e32 v[42:43], v[10:11]
	v_mov_b64_e32 v[40:41], v[8:9]
	v_mov_b64_e32 v[38:39], v[6:7]
	v_mov_b64_e32 v[36:37], v[4:5]
	s_waitcnt vmcnt(0)
	v_mov_b32_e32 v55, v3

; template <class Map>
; DI void p0_transpose(const float* W, int K, int N, bf16_t* WT, const float* gain, const Map map, LAS float* scr, int& base, int gw, int NGW, int lane) {
;     ...
;         const int kb = it / nblk, nb = it % nblk, k0 = 64 * kb, c = 32 * nb + (lane & 31);
;         const float* p = W + (size_t)(k0 + (lane >> 5)) * N + c;
; #pragma unroll
;         for (int i = 0; i < 32; ++i) dst[i] = (c < N) ? p[(size_t)(2 * i) * N] : 0.f;
.LBB0_89:
	s_waitcnt vmcnt(1)
	v_add_co_u32_e32 v4, vcc, 0x6e000, v122
	s_waitcnt vmcnt(0)
	s_nop 0
	v_addc_co_u32_e32 v5, vcc, 0, v123, vcc
	v_add_co_u32_e32 v6, vcc, 0x73000, v122
	s_nop 1
	v_addc_co_u32_e32 v7, vcc, 0, v123, vcc
	v_mov_b32_e32 v56, v224
	v_mov_b32_e32 v3, v225
	s_waitcnt vmcnt(1)
	v_mov_b64_e32 v[4:5], v[36:37]
	v_mov_b64_e32 v[24:25], v[56:57]
	v_mov_b64_e32 v[6:7], v[38:39]
	v_mov_b64_e32 v[8:9], v[40:41]
	v_mov_b64_e32 v[10:11], v[42:43]
	v_mov_b64_e32 v[12:13], v[44:45]
	v_mov_b64_e32 v[14:15], v[46:47]
	v_mov_b64_e32 v[16:17], v[48:49]
	v_mov_b64_e32 v[18:19], v[50:51]
	v_mov_b64_e32 v[20:21], v[52:53]
	v_mov_b64_e32 v[22:23], v[54:55]
	v_mov_b64_e32 v[26:27], v[58:59]
	v_mov_b64_e32 v[28:29], v[60:61]
	v_mov_b64_e32 v[30:31], v[62:63]
	v_mov_b64_e32 v[32:33], v[64:65]
	v_mov_b64_e32 v[34:35], v[66:67]
	s_waitcnt vmcnt(0)
	v_mov_b32_e32 v25, v3

; template <class Map>
; DI void p0_transpose(const float* W, int K, int N, bf16_t* WT, const float* gain, const Map map, LAS float* scr, int& base, int gw, int NGW, int lane) {
;     ...
;         const int kb = it / nblk, nb = it % nblk, k0 = 64 * kb, c = 32 * nb + (lane & 31);
;         const float* p = W + (size_t)(k0 + (lane >> 5)) * N + c;
; #pragma unroll
;         for (int i = 0; i < 32; ++i) dst[i] = (c < N) ? p[(size_t)(2 * i) * N] : 0.f;
.LBB0_93:
	v_add_co_u32_e32 v36, vcc, 0x79000, v122
	s_nop 1
	v_addc_co_u32_e32 v37, vcc, 0, v123, vcc
	v_add_co_u32_e32 v38, vcc, 0x7e000, v122
	s_nop 1
	v_addc_co_u32_e32 v39, vcc, 0, v123, vcc
	v_mov_b32_e32 v26, v226
	v_mov_b32_e32 v3, v227
	s_waitcnt vmcnt(1)
	v_mov_b64_e32 v[66:67], v[34:35]
	v_mov_b64_e32 v[58:59], v[26:27]
	v_mov_b64_e32 v[64:65], v[32:33]
	v_mov_b64_e32 v[62:63], v[30:31]
	v_mov_b64_e32 v[60:61], v[28:29]
	v_mov_b64_e32 v[56:57], v[24:25]
	v_mov_b64_e32 v[54:55], v[22:23]
	v_mov_b64_e32 v[52:53], v[20:21]
	v_mov_b64_e32 v[50:51], v[18:19]
	v_mov_b64_e32 v[48:49], v[16:17]
	v_mov_b64_e32 v[46:47], v[14:15]
	v_mov_b64_e32 v[44:45], v[12:13]
	v_mov_b64_e32 v[42:43], v[10:11]
	v_mov_b64_e32 v[40:41], v[8:9]
	v_mov_b64_e32 v[38:39], v[6:7]
	v_mov_b64_e32 v[36:37], v[4:5]
	s_waitcnt vmcnt(0)
	v_mov_b32_e32 v59, v3

; template <class Map>
; DI void p0_transpose(const float* W, int K, int N, bf16_t* WT, const float* gain, const Map map, LAS float* scr, int& base, int gw, int NGW, int lane) {
;     ...
;         const int kb = it / nblk, nb = it % nblk, k0 = 64 * kb, c = 32 * nb + (lane & 31);
;         const float* p = W + (size_t)(k0 + (lane >> 5)) * N + c;
; #pragma unroll
;         for (int i = 0; i < 32; ++i) dst[i] = (c < N) ? p[(size_t)(2 * i) * N] : 0.f;
.LBB0_97:
	s_waitcnt vmcnt(1)
	v_add_co_u32_e32 v4, vcc, 0x84000, v122
	s_waitcnt vmcnt(0)
	s_nop 0
	v_addc_co_u32_e32 v5, vcc, 0, v123, vcc
	v_add_co_u32_e32 v6, vcc, 0x89000, v122
	s_nop 1
	v_addc_co_u32_e32 v7, vcc, 0, v123, vcc
	v_mov_b32_e32 v60, v228
	v_mov_b32_e32 v3, v229
	s_waitcnt vmcnt(1)
	v_mov_b64_e32 v[4:5], v[36:37]
	v_mov_b64_e32 v[28:29], v[60:61]
	v_mov_b64_e32 v[6:7], v[38:39]
	v_mov_b64_e32 v[8:9], v[40:41]
	v_mov_b64_e32 v[10:11], v[42:43]
	v_mov_b64_e32 v[12:13], v[44:45]
	v_mov_b64_e32 v[14:15], v[46:47]
	v_mov_b64_e32 v[16:17], v[48:49]
	v_mov_b64_e32 v[18:19], v[50:51]
	v_mov_b64_e32 v[20:21], v[52:53]
	v_mov_b64_e32 v[22:23], v[54:55]
	v_mov_b64_e32 v[24:25], v[56:57]
	v_mov_b64_e32 v[26:27], v[58:59]
	v_mov_b64_e32 v[30:31], v[62:63]
	v_mov_b64_e32 v[32:33], v[64:65]
	v_mov_b64_e32 v[34:35], v[66:67]
	s_waitcnt vmcnt(0)
	v_mov_b32_e32 v29, v3

; template <class Map>
; DI void p0_transpose(const float* W, int K, int N, bf16_t* WT, const float* gain, const Map map, LAS float* scr, int& base, int gw, int NGW, int lane) {
;     ...
;         const int kb = it / nblk, nb = it % nblk, k0 = 64 * kb, c = 32 * nb + (lane & 31);
;         const float* p = W + (size_t)(k0 + (lane >> 5)) * N + c;
; #pragma unroll
;         for (int i = 0; i < 32; ++i) dst[i] = (c < N) ? p[(size_t)(2 * i) * N] : 0.f;
.LBB0_101:
	v_add_co_u32_e32 v36, vcc, 0x8f000, v122
	s_nop 1
	v_addc_co_u32_e32 v37, vcc, 0, v123, vcc
	v_add_co_u32_e32 v38, vcc, 0x94000, v122
	s_nop 1
	v_addc_co_u32_e32 v39, vcc, 0, v123, vcc
	v_mov_b32_e32 v30, v230
	v_mov_b32_e32 v3, v231
	s_waitcnt vmcnt(1)
	v_mov_b64_e32 v[98:99], v[34:35]
	v_mov_b64_e32 v[94:95], v[30:31]
	v_mov_b64_e32 v[96:97], v[32:33]
	v_mov_b64_e32 v[92:93], v[28:29]
	v_mov_b64_e32 v[90:91], v[26:27]
	v_mov_b64_e32 v[88:89], v[24:25]
	v_mov_b64_e32 v[86:87], v[22:23]
	v_mov_b64_e32 v[84:85], v[20:21]
	v_mov_b64_e32 v[82:83], v[18:19]
	v_mov_b64_e32 v[80:81], v[16:17]
	v_mov_b64_e32 v[78:79], v[14:15]
	v_mov_b64_e32 v[76:77], v[12:13]
	v_mov_b64_e32 v[74:75], v[10:11]
	v_mov_b64_e32 v[72:73], v[8:9]
	v_mov_b64_e32 v[70:71], v[6:7]
	v_mov_b64_e32 v[68:69], v[4:5]
	s_waitcnt vmcnt(0)
	v_mov_b32_e32 v95, v3

; template <class Map>
; DI void p0_transpose(const float* W, int K, int N, bf16_t* WT, const float* gain, const Map map, LAS float* scr, int& base, int gw, int NGW, int lane) {
;     ...
;         const int kb = it / nblk, nb = it % nblk, k0 = 64 * kb, c = 32 * nb + (lane & 31);
;         const float* p = W + (size_t)(k0 + (lane >> 5)) * N + c;
; #pragma unroll
;         for (int i = 0; i < 32; ++i) dst[i] = (c < N) ? p[(size_t)(2 * i) * N] : 0.f;
.LBB0_105:
	s_waitcnt vmcnt(1)
	v_add_co_u32_e32 v4, vcc, 0x9a000, v122
	s_waitcnt vmcnt(0)
	s_nop 0
	v_addc_co_u32_e32 v5, vcc, 0, v123, vcc
	v_add_co_u32_e32 v6, vcc, 0x9f000, v122
	s_nop 1
	v_addc_co_u32_e32 v7, vcc, 0, v123, vcc
	v_mov_b32_e32 v96, v232
	v_mov_b32_e32 v3, v233
	s_waitcnt vmcnt(1)
	v_mov_b64_e32 v[36:37], v[68:69]
	v_mov_b64_e32 v[64:65], v[96:97]
	v_mov_b64_e32 v[38:39], v[70:71]
	v_mov_b64_e32 v[40:41], v[72:73]
	v_mov_b64_e32 v[42:43], v[74:75]
	v_mov_b64_e32 v[44:45], v[76:77]
	v_mov_b64_e32 v[46:47], v[78:79]
	v_mov_b64_e32 v[48:49], v[80:81]
	v_mov_b64_e32 v[50:51], v[82:83]
	v_mov_b64_e32 v[52:53], v[84:85]
	v_mov_b64_e32 v[54:55], v[86:87]
	v_mov_b64_e32 v[56:57], v[88:89]
	v_mov_b64_e32 v[58:59], v[90:91]
	v_mov_b64_e32 v[60:61], v[92:93]
	v_mov_b64_e32 v[62:63], v[94:95]
	v_mov_b64_e32 v[66:67], v[98:99]
	s_waitcnt vmcnt(0)
	v_mov_b32_e32 v65, v3

; template <class Map>
; DI void p0_transpose(const float* W, int K, int N, bf16_t* WT, const float* gain, const Map map, LAS float* scr, int& base, int gw, int NGW, int lane) {
;     ...
;         const int kb = it / nblk, nb = it % nblk, k0 = 64 * kb, c = 32 * nb + (lane & 31);
;         const float* p = W + (size_t)(k0 + (lane >> 5)) * N + c;
; #pragma unroll
;         for (int i = 0; i < 32; ++i) dst[i] = (c < N) ? p[(size_t)(2 * i) * N] : 0.f;
.LBB0_109:
	s_waitcnt vmcnt(1)
	v_add_co_u32_e32 v4, vcc, 0xa5000, v122
	s_waitcnt vmcnt(0)
	s_nop 0
	v_addc_co_u32_e32 v5, vcc, 0, v123, vcc
	v_add_co_u32_e32 v6, vcc, 0xaa000, v122
	s_nop 1
	v_addc_co_u32_e32 v7, vcc, 0, v123, vcc
	v_mov_b32_e32 v66, v234
	v_mov_b32_e32 v3, v235
	s_waitcnt vmcnt(1)
	v_mov_b64_e32 v[4:5], v[36:37]
	v_mov_b64_e32 v[34:35], v[66:67]
	v_mov_b64_e32 v[6:7], v[38:39]
	v_mov_b64_e32 v[8:9], v[40:41]
	v_mov_b64_e32 v[10:11], v[42:43]
	v_mov_b64_e32 v[12:13], v[44:45]
	v_mov_b64_e32 v[14:15], v[46:47]
	v_mov_b64_e32 v[16:17], v[48:49]
	v_mov_b64_e32 v[18:19], v[50:51]
	v_mov_b64_e32 v[20:21], v[52:53]
	v_mov_b64_e32 v[22:23], v[54:55]
	v_mov_b64_e32 v[24:25], v[56:57]
	v_mov_b64_e32 v[26:27], v[58:59]
	v_mov_b64_e32 v[28:29], v[60:61]
	v_mov_b64_e32 v[30:31], v[62:63]
	v_mov_b64_e32 v[32:33], v[64:65]
	s_waitcnt vmcnt(0)
	v_mov_b32_e32 v35, v3

; template <class Map>
; DI void p0_transpose(const float* W, int K, int N, bf16_t* WT, const float* gain, const Map map, LAS float* scr, int& base, int gw, int NGW, int lane) {
;     ...
;     auto loadit = [&](int it, float (&dst)[32]) {
;         const int kb = it / nblk, nb = it % nblk, k0 = 64 * kb, c = 32 * nb + (lane & 31);
;         const float* p = W + (size_t)(k0 + (lane >> 5)) * N + c;
; #pragma unroll
;         for (int i = 0; i < 32; ++i) dst[i] = (c < N) ? p[(size_t)(2 * i) * N] : 0.f;
;     };
;     if (first < nitems) loadit(first, cur);
;     for (int it = first; it < nitems; it += NGW) {
;         const bool more = it + NGW < nitems;
;         if (more) loadit(it + NGW, nxt);
.LBB0_185:
	s_or_saveexec_b64 s[90:91], s[90:91]
	v_lshl_or_b32 v3, s54, 6, v100
	v_mov_b64_e32 v[38:39], s[82:83]
	v_mad_i64_i32 v[38:39], s[54:55], v3, s39, v[38:39]
	v_ashrrev_i32_e32 v37, 31, v36
	v_lshl_add_u64 v[122:123], v[36:37], 2, v[38:39]
	s_mov_b32 s94, 0x5800
	s_mov_b32 s95, 0
	v_mov_b32_e32 v236, v122
	v_mov_b32_e32 v237, v123
	global_load_dword v204, v[236:237], off
	v_lshl_add_u64 v[236:237], v[236:237], 0, s[94:95]
	global_load_dword v205, v[236:237], off
	v_lshl_add_u64 v[236:237], v[236:237], 0, s[94:95]
	global_load_dword v206, v[236:237], off
	v_lshl_add_u64 v[236:237], v[236:237], 0, s[94:95]
	global_load_dword v207, v[236:237], off
	v_lshl_add_u64 v[236:237], v[236:237], 0, s[94:95]
	global_load_dword v208, v[236:237], off
	v_lshl_add_u64 v[236:237], v[236:237], 0, s[94:95]
	global_load_dword v209, v[236:237], off
	v_lshl_add_u64 v[236:237], v[236:237], 0, s[94:95]
	global_load_dword v210, v[236:237], off
	v_lshl_add_u64 v[236:237], v[236:237], 0, s[94:95]
	global_load_dword v211, v[236:237], off
	v_lshl_add_u64 v[236:237], v[236:237], 0, s[94:95]
	global_load_dword v212, v[236:237], off
	v_lshl_add_u64 v[236:237], v[236:237], 0, s[94:95]
	global_load_dword v213, v[236:237], off
	v_lshl_add_u64 v[236:237], v[236:237], 0, s[94:95]
	global_load_dword v214, v[236:237], off
	v_lshl_add_u64 v[236:237], v[236:237], 0, s[94:95]
	global_load_dword v215, v[236:237], off
	v_lshl_add_u64 v[236:237], v[236:237], 0, s[94:95]
	global_load_dword v216, v[236:237], off
	v_lshl_add_u64 v[236:237], v[236:237], 0, s[94:95]
	global_load_dword v217, v[236:237], off
	v_lshl_add_u64 v[236:237], v[236:237], 0, s[94:95]
	global_load_dword v218, v[236:237], off
	v_lshl_add_u64 v[236:237], v[236:237], 0, s[94:95]
	global_load_dword v219, v[236:237], off
	v_lshl_add_u64 v[236:237], v[236:237], 0, s[94:95]
	global_load_dword v220, v[236:237], off
	v_lshl_add_u64 v[236:237], v[236:237], 0, s[94:95]
	global_load_dword v221, v[236:237], off
	v_lshl_add_u64 v[236:237], v[236:237], 0, s[94:95]
	global_load_dword v222, v[236:237], off
	v_lshl_add_u64 v[236:237], v[236:237], 0, s[94:95]
	global_load_dword v223, v[236:237], off
	v_lshl_add_u64 v[236:237], v[236:237], 0, s[94:95]
	global_load_dword v224, v[236:237], off
	v_lshl_add_u64 v[236:237], v[236:237], 0, s[94:95]
	global_load_dword v225, v[236:237], off
	v_lshl_add_u64 v[236:237], v[236:237], 0, s[94:95]
	global_load_dword v226, v[236:237], off
	v_lshl_add_u64 v[236:237], v[236:237], 0, s[94:95]
	global_load_dword v227, v[236:237], off
	v_lshl_add_u64 v[236:237], v[236:237], 0, s[94:95]
	global_load_dword v228, v[236:237], off
	v_lshl_add_u64 v[236:237], v[236:237], 0, s[94:95]
	global_load_dword v229, v[236:237], off
	v_lshl_add_u64 v[236:237], v[236:237], 0, s[94:95]
	global_load_dword v230, v[236:237], off
	v_lshl_add_u64 v[236:237], v[236:237], 0, s[94:95]
	global_load_dword v231, v[236:237], off
	v_lshl_add_u64 v[236:237], v[236:237], 0, s[94:95]
	global_load_dword v232, v[236:237], off
	v_lshl_add_u64 v[236:237], v[236:237], 0, s[94:95]
	global_load_dword v233, v[236:237], off
	v_lshl_add_u64 v[236:237], v[236:237], 0, s[94:95]
	global_load_dword v234, v[236:237], off
	v_lshl_add_u64 v[236:237], v[236:237], 0, s[94:95]
	global_load_dword v235, v[236:237], off
	s_waitcnt vmcnt(0)
	s_waitcnt vmcnt(4)
	v_mov_b32_e32 v5, 0
	s_xor_b64 exec, exec, s[90:91]
	s_cbranch_execz .LBB0_187
	v_add_co_u32_e32 v6, vcc, 0x5000, v122
	s_nop 1
	v_addc_co_u32_e32 v7, vcc, 0, v123, vcc
	v_mov_b32_e32 v4, v204
	v_mov_b32_e32 v5, v205

; template <class Map>
; DI void p0_transpose(const float* W, int K, int N, bf16_t* WT, const float* gain, const Map map, LAS float* scr, int& base, int gw, int NGW, int lane) {
;     ...
;     auto loadit = [&](int it, float (&dst)[32]) {
;         const int kb = it / nblk, nb = it % nblk, k0 = 64 * kb, c = 32 * nb + (lane & 31);
;         const float* p = W + (size_t)(k0 + (lane >> 5)) * N + c;
; #pragma unroll
;         for (int i = 0; i < 32; ++i) dst[i] = (c < N) ? p[(size_t)(2 * i) * N] : 0.f;
;     };
;     if (first < nitems) loadit(first, cur);
;     for (int it = first; it < nitems; it += NGW) {
;         const bool more = it + NGW < nitems;
;         if (more) loadit(it + NGW, nxt);
.LBB0_322:
	s_or_saveexec_b64 s[82:83], s[82:83]
	v_lshl_or_b32 v38, s53, 6, v100
	v_ashrrev_i32_e32 v39, 31, v38
	v_lshlrev_b64 v[38:39], 12, v[38:39]
	v_lshl_add_u64 v[38:39], s[34:35], 0, v[38:39]
	v_ashrrev_i32_e32 v37, 31, v36
	v_lshl_add_u64 v[106:107], v[36:37], 2, v[38:39]
	s_mov_b32 s94, 0x2000
	s_mov_b32 s95, 0
	v_mov_b32_e32 v236, v106
	v_mov_b32_e32 v237, v107
	global_load_dword v204, v[236:237], off
	v_lshl_add_u64 v[236:237], v[236:237], 0, s[94:95]
	global_load_dword v205, v[236:237], off
	v_lshl_add_u64 v[236:237], v[236:237], 0, s[94:95]
	global_load_dword v206, v[236:237], off
	v_lshl_add_u64 v[236:237], v[236:237], 0, s[94:95]
	global_load_dword v207, v[236:237], off
	v_lshl_add_u64 v[236:237], v[236:237], 0, s[94:95]
	global_load_dword v208, v[236:237], off
	v_lshl_add_u64 v[236:237], v[236:237], 0, s[94:95]
	global_load_dword v209, v[236:237], off
	v_lshl_add_u64 v[236:237], v[236:237], 0, s[94:95]
	global_load_dword v210, v[236:237], off
	v_lshl_add_u64 v[236:237], v[236:237], 0, s[94:95]
	global_load_dword v211, v[236:237], off
	v_lshl_add_u64 v[236:237], v[236:237], 0, s[94:95]
	global_load_dword v212, v[236:237], off
	v_lshl_add_u64 v[236:237], v[236:237], 0, s[94:95]
	global_load_dword v213, v[236:237], off
	v_lshl_add_u64 v[236:237], v[236:237], 0, s[94:95]
	global_load_dword v214, v[236:237], off
	v_lshl_add_u64 v[236:237], v[236:237], 0, s[94:95]
	global_load_dword v215, v[236:237], off
	v_lshl_add_u64 v[236:237], v[236:237], 0, s[94:95]
	global_load_dword v216, v[236:237], off
	v_lshl_add_u64 v[236:237], v[236:237], 0, s[94:95]
	global_load_dword v217, v[236:237], off
	v_lshl_add_u64 v[236:237], v[236:237], 0, s[94:95]
	global_load_dword v218, v[236:237], off
	v_lshl_add_u64 v[236:237], v[236:237], 0, s[94:95]
	global_load_dword v219, v[236:237], off
	v_lshl_add_u64 v[236:237], v[236:237], 0, s[94:95]
	global_load_dword v220, v[236:237], off
	v_lshl_add_u64 v[236:237], v[236:237], 0, s[94:95]
	global_load_dword v221, v[236:237], off
	v_lshl_add_u64 v[236:237], v[236:237], 0, s[94:95]
	global_load_dword v222, v[236:237], off
	v_lshl_add_u64 v[236:237], v[236:237], 0, s[94:95]
	global_load_dword v223, v[236:237], off
	v_lshl_add_u64 v[236:237], v[236:237], 0, s[94:95]
	global_load_dword v224, v[236:237], off
	v_lshl_add_u64 v[236:237], v[236:237], 0, s[94:95]
	global_load_dword v225, v[236:237], off
	v_lshl_add_u64 v[236:237], v[236:237], 0, s[94:95]
	global_load_dword v226, v[236:237], off
	v_lshl_add_u64 v[236:237], v[236:237], 0, s[94:95]
	global_load_dword v227, v[236:237], off
	v_lshl_add_u64 v[236:237], v[236:237], 0, s[94:95]
	global_load_dword v228, v[236:237], off
	v_lshl_add_u64 v[236:237], v[236:237], 0, s[94:95]
	global_load_dword v229, v[236:237], off
	v_lshl_add_u64 v[236:237], v[236:237], 0, s[94:95]
	global_load_dword v230, v[236:237], off
	v_lshl_add_u64 v[236:237], v[236:237], 0, s[94:95]
	global_load_dword v231, v[236:237], off
	v_lshl_add_u64 v[236:237], v[236:237], 0, s[94:95]
	global_load_dword v232, v[236:237], off
	v_lshl_add_u64 v[236:237], v[236:237], 0, s[94:95]
	global_load_dword v233, v[236:237], off
	v_lshl_add_u64 v[236:237], v[236:237], 0, s[94:95]
	global_load_dword v234, v[236:237], off
	v_lshl_add_u64 v[236:237], v[236:237], 0, s[94:95]
	global_load_dword v235, v[236:237], off
	s_waitcnt vmcnt(0)
	s_waitcnt vmcnt(0)
	v_mov_b32_e32 v5, 0
	s_xor_b64 exec, exec, s[82:83]
	s_cbranch_execz .LBB0_324
	v_add_co_u32_e32 v6, vcc, 0x2000, v106
	s_nop 1
	v_addc_co_u32_e32 v7, vcc, 0, v107, vcc
	v_mov_b32_e32 v4, v204
	v_mov_b32_e32 v5, v205

; template <class Map>
; DI void p0_transpose(const float* W, int K, int N, bf16_t* WT, const float* gain, const Map map, LAS float* scr, int& base, int gw, int NGW, int lane) {
;     ...
;         const int kb = it / nblk, nb = it % nblk, k0 = 64 * kb, c = 32 * nb + (lane & 31);
;         const float* p = W + (size_t)(k0 + (lane >> 5)) * N + c;
; #pragma unroll
;         for (int i = 0; i < 32; ++i) dst[i] = (c < N) ? p[(size_t)(2 * i) * N] : 0.f;
.LBB0_327:
	v_add_co_u32_e32 v36, vcc, 0x4000, v106
	s_nop 1
	v_addc_co_u32_e32 v37, vcc, 0, v107, vcc
	v_add_co_u32_e32 v38, vcc, 0x6000, v106
	s_nop 1
	v_addc_co_u32_e32 v39, vcc, 0, v107, vcc
	v_mov_b32_e32 v6, v206
	v_mov_b32_e32 v3, v207
	s_waitcnt vmcnt(1)
	v_mov_b64_e32 v[66:67], v[34:35]
	v_mov_b64_e32 v[38:39], v[6:7]
	v_mov_b64_e32 v[64:65], v[32:33]
	v_mov_b64_e32 v[62:63], v[30:31]
	v_mov_b64_e32 v[60:61], v[28:29]
	v_mov_b64_e32 v[58:59], v[26:27]
	v_mov_b64_e32 v[56:57], v[24:25]
	v_mov_b64_e32 v[54:55], v[22:23]
	v_mov_b64_e32 v[52:53], v[20:21]
	v_mov_b64_e32 v[50:51], v[18:19]
	v_mov_b64_e32 v[48:49], v[16:17]
	v_mov_b64_e32 v[46:47], v[14:15]
	v_mov_b64_e32 v[44:45], v[12:13]
	v_mov_b64_e32 v[42:43], v[10:11]
	v_mov_b64_e32 v[40:41], v[8:9]
	v_mov_b64_e32 v[36:37], v[4:5]
	s_waitcnt vmcnt(0)
	v_mov_b32_e32 v39, v3

; template <class Map>
; DI void p0_transpose(const float* W, int K, int N, bf16_t* WT, const float* gain, const Map map, LAS float* scr, int& base, int gw, int NGW, int lane) {
;     ...
;         const int kb = it / nblk, nb = it % nblk, k0 = 64 * kb, c = 32 * nb + (lane & 31);
;         const float* p = W + (size_t)(k0 + (lane >> 5)) * N + c;
; #pragma unroll
;         for (int i = 0; i < 32; ++i) dst[i] = (c < N) ? p[(size_t)(2 * i) * N] : 0.f;
.LBB0_331:
	s_waitcnt vmcnt(1)
	v_add_co_u32_e32 v4, vcc, 0x8000, v106
	s_waitcnt vmcnt(0)
	s_nop 0
	v_addc_co_u32_e32 v5, vcc, 0, v107, vcc
	v_add_co_u32_e32 v6, vcc, 0xa000, v106
	s_nop 1
	v_addc_co_u32_e32 v7, vcc, 0, v107, vcc
	v_mov_b32_e32 v40, v208
	v_mov_b32_e32 v3, v209
	s_waitcnt vmcnt(1)
	v_mov_b64_e32 v[4:5], v[36:37]
	v_mov_b64_e32 v[8:9], v[40:41]
	v_mov_b64_e32 v[6:7], v[38:39]
	v_mov_b64_e32 v[10:11], v[42:43]
	v_mov_b64_e32 v[12:13], v[44:45]
	v_mov_b64_e32 v[14:15], v[46:47]
	v_mov_b64_e32 v[16:17], v[48:49]
	v_mov_b64_e32 v[18:19], v[50:51]
	v_mov_b64_e32 v[20:21], v[52:53]
	v_mov_b64_e32 v[22:23], v[54:55]
	v_mov_b64_e32 v[24:25], v[56:57]
	v_mov_b64_e32 v[26:27], v[58:59]
	v_mov_b64_e32 v[28:29], v[60:61]
	v_mov_b64_e32 v[30:31], v[62:63]
	v_mov_b64_e32 v[32:33], v[64:65]
	v_mov_b64_e32 v[34:35], v[66:67]
	s_waitcnt vmcnt(0)
	v_mov_b32_e32 v9, v3

; template <class Map>
; DI void p0_transpose(const float* W, int K, int N, bf16_t* WT, const float* gain, const Map map, LAS float* scr, int& base, int gw, int NGW, int lane) {
;     ...
;         const int kb = it / nblk, nb = it % nblk, k0 = 64 * kb, c = 32 * nb + (lane & 31);
;         const float* p = W + (size_t)(k0 + (lane >> 5)) * N + c;
; #pragma unroll
;         for (int i = 0; i < 32; ++i) dst[i] = (c < N) ? p[(size_t)(2 * i) * N] : 0.f;
.LBB0_335:
	v_add_co_u32_e32 v36, vcc, 0xc000, v106
	s_nop 1
	v_addc_co_u32_e32 v37, vcc, 0, v107, vcc
	v_add_co_u32_e32 v38, vcc, 0xe000, v106
	s_nop 1
	v_addc_co_u32_e32 v39, vcc, 0, v107, vcc
	v_mov_b32_e32 v10, v210
	v_mov_b32_e32 v3, v211
	s_waitcnt vmcnt(1)
	v_mov_b64_e32 v[66:67], v[34:35]
	v_mov_b64_e32 v[42:43], v[10:11]
	v_mov_b64_e32 v[64:65], v[32:33]
	v_mov_b64_e32 v[62:63], v[30:31]
	v_mov_b64_e32 v[60:61], v[28:29]
	v_mov_b64_e32 v[58:59], v[26:27]
	v_mov_b64_e32 v[56:57], v[24:25]
	v_mov_b64_e32 v[54:55], v[22:23]
	v_mov_b64_e32 v[52:53], v[20:21]
	v_mov_b64_e32 v[50:51], v[18:19]
	v_mov_b64_e32 v[48:49], v[16:17]
	v_mov_b64_e32 v[46:47], v[14:15]
	v_mov_b64_e32 v[44:45], v[12:13]
	v_mov_b64_e32 v[40:41], v[8:9]
	v_mov_b64_e32 v[38:39], v[6:7]
	v_mov_b64_e32 v[36:37], v[4:5]
	s_waitcnt vmcnt(0)
	v_mov_b32_e32 v43, v3

; template <class Map>
; DI void p0_transpose(const float* W, int K, int N, bf16_t* WT, const float* gain, const Map map, LAS float* scr, int& base, int gw, int NGW, int lane) {
;     ...
;         const int kb = it / nblk, nb = it % nblk, k0 = 64 * kb, c = 32 * nb + (lane & 31);
;         const float* p = W + (size_t)(k0 + (lane >> 5)) * N + c;
; #pragma unroll
;         for (int i = 0; i < 32; ++i) dst[i] = (c < N) ? p[(size_t)(2 * i) * N] : 0.f;
.LBB0_339:
	s_waitcnt vmcnt(1)
	v_add_co_u32_e32 v4, vcc, 0x10000, v106
	s_waitcnt vmcnt(0)
	s_nop 0
	v_addc_co_u32_e32 v5, vcc, 0, v107, vcc
	v_add_co_u32_e32 v6, vcc, 0x12000, v106
	s_nop 1
	v_addc_co_u32_e32 v7, vcc, 0, v107, vcc
	v_mov_b32_e32 v44, v212
	v_mov_b32_e32 v3, v213
	s_waitcnt vmcnt(1)
	v_mov_b64_e32 v[4:5], v[36:37]
	v_mov_b64_e32 v[12:13], v[44:45]
	v_mov_b64_e32 v[6:7], v[38:39]
	v_mov_b64_e32 v[8:9], v[40:41]
	v_mov_b64_e32 v[10:11], v[42:43]
	v_mov_b64_e32 v[14:15], v[46:47]
	v_mov_b64_e32 v[16:17], v[48:49]
	v_mov_b64_e32 v[18:19], v[50:51]
	v_mov_b64_e32 v[20:21], v[52:53]
	v_mov_b64_e32 v[22:23], v[54:55]
	v_mov_b64_e32 v[24:25], v[56:57]
	v_mov_b64_e32 v[26:27], v[58:59]
	v_mov_b64_e32 v[28:29], v[60:61]
	v_mov_b64_e32 v[30:31], v[62:63]
	v_mov_b64_e32 v[32:33], v[64:65]
	v_mov_b64_e32 v[34:35], v[66:67]
	s_waitcnt vmcnt(0)
	v_mov_b32_e32 v13, v3

; template <class Map>
; DI void p0_transpose(const float* W, int K, int N, bf16_t* WT, const float* gain, const Map map, LAS float* scr, int& base, int gw, int NGW, int lane) {
;     ...
;         const int kb = it / nblk, nb = it % nblk, k0 = 64 * kb, c = 32 * nb + (lane & 31);
;         const float* p = W + (size_t)(k0 + (lane >> 5)) * N + c;
; #pragma unroll
;         for (int i = 0; i < 32; ++i) dst[i] = (c < N) ? p[(size_t)(2 * i) * N] : 0.f;
.LBB0_343:
	v_add_co_u32_e32 v36, vcc, 0x14000, v106
	s_nop 1
	v_addc_co_u32_e32 v37, vcc, 0, v107, vcc
	v_add_co_u32_e32 v38, vcc, 0x16000, v106
	s_nop 1
	v_addc_co_u32_e32 v39, vcc, 0, v107, vcc
	v_mov_b32_e32 v14, v214
	v_mov_b32_e32 v3, v215
	s_waitcnt vmcnt(1)
	v_mov_b64_e32 v[66:67], v[34:35]
	v_mov_b64_e32 v[46:47], v[14:15]
	v_mov_b64_e32 v[64:65], v[32:33]
	v_mov_b64_e32 v[62:63], v[30:31]
	v_mov_b64_e32 v[60:61], v[28:29]
	v_mov_b64_e32 v[58:59], v[26:27]
	v_mov_b64_e32 v[56:57], v[24:25]
	v_mov_b64_e32 v[54:55], v[22:23]
	v_mov_b64_e32 v[52:53], v[20:21]
	v_mov_b64_e32 v[50:51], v[18:19]
	v_mov_b64_e32 v[48:49], v[16:17]
	v_mov_b64_e32 v[44:45], v[12:13]
	v_mov_b64_e32 v[42:43], v[10:11]
	v_mov_b64_e32 v[40:41], v[8:9]
	v_mov_b64_e32 v[38:39], v[6:7]
	v_mov_b64_e32 v[36:37], v[4:5]
	s_waitcnt vmcnt(0)
	v_mov_b32_e32 v47, v3

; template <class Map>
; DI void p0_transpose(const float* W, int K, int N, bf16_t* WT, const float* gain, const Map map, LAS float* scr, int& base, int gw, int NGW, int lane) {
;     ...
;         const int kb = it / nblk, nb = it % nblk, k0 = 64 * kb, c = 32 * nb + (lane & 31);
;         const float* p = W + (size_t)(k0 + (lane >> 5)) * N + c;
; #pragma unroll
;         for (int i = 0; i < 32; ++i) dst[i] = (c < N) ? p[(size_t)(2 * i) * N] : 0.f;
.LBB0_347:
	s_waitcnt vmcnt(1)
	v_add_co_u32_e32 v4, vcc, 0x18000, v106
	s_waitcnt vmcnt(0)
	s_nop 0
	v_addc_co_u32_e32 v5, vcc, 0, v107, vcc
	v_add_co_u32_e32 v6, vcc, 0x1a000, v106
	s_nop 1
	v_addc_co_u32_e32 v7, vcc, 0, v107, vcc
	v_mov_b32_e32 v48, v216
	v_mov_b32_e32 v3, v217
	s_waitcnt vmcnt(1)
	v_mov_b64_e32 v[4:5], v[36:37]
	v_mov_b64_e32 v[16:17], v[48:49]
	v_mov_b64_e32 v[6:7], v[38:39]
	v_mov_b64_e32 v[8:9], v[40:41]
	v_mov_b64_e32 v[10:11], v[42:43]
	v_mov_b64_e32 v[12:13], v[44:45]
	v_mov_b64_e32 v[14:15], v[46:47]
	v_mov_b64_e32 v[18:19], v[50:51]
	v_mov_b64_e32 v[20:21], v[52:53]
	v_mov_b64_e32 v[22:23], v[54:55]
	v_mov_b64_e32 v[24:25], v[56:57]
	v_mov_b64_e32 v[26:27], v[58:59]
	v_mov_b64_e32 v[28:29], v[60:61]
	v_mov_b64_e32 v[30:31], v[62:63]
	v_mov_b64_e32 v[32:33], v[64:65]
	v_mov_b64_e32 v[34:35], v[66:67]
	s_waitcnt vmcnt(0)
	v_mov_b32_e32 v17, v3

; template <class Map>
; DI void p0_transpose(const float* W, int K, int N, bf16_t* WT, const float* gain, const Map map, LAS float* scr, int& base, int gw, int NGW, int lane) {
;     ...
;         const int kb = it / nblk, nb = it % nblk, k0 = 64 * kb, c = 32 * nb + (lane & 31);
;         const float* p = W + (size_t)(k0 + (lane >> 5)) * N + c;
; #pragma unroll
;         for (int i = 0; i < 32; ++i) dst[i] = (c < N) ? p[(size_t)(2 * i) * N] : 0.f;
.LBB0_351:
	v_add_co_u32_e32 v36, vcc, 0x1c000, v106
	s_nop 1
	v_addc_co_u32_e32 v37, vcc, 0, v107, vcc
	v_add_co_u32_e32 v38, vcc, 0x1e000, v106
	s_nop 1
	v_addc_co_u32_e32 v39, vcc, 0, v107, vcc
	v_mov_b32_e32 v18, v218
	v_mov_b32_e32 v3, v219
	s_waitcnt vmcnt(1)
	v_mov_b64_e32 v[66:67], v[34:35]
	v_mov_b64_e32 v[50:51], v[18:19]
	v_mov_b64_e32 v[64:65], v[32:33]
	v_mov_b64_e32 v[62:63], v[30:31]
	v_mov_b64_e32 v[60:61], v[28:29]
	v_mov_b64_e32 v[58:59], v[26:27]
	v_mov_b64_e32 v[56:57], v[24:25]
	v_mov_b64_e32 v[54:55], v[22:23]
	v_mov_b64_e32 v[52:53], v[20:21]
	v_mov_b64_e32 v[48:49], v[16:17]
	v_mov_b64_e32 v[46:47], v[14:15]
	v_mov_b64_e32 v[44:45], v[12:13]
	v_mov_b64_e32 v[42:43], v[10:11]
	v_mov_b64_e32 v[40:41], v[8:9]
	v_mov_b64_e32 v[38:39], v[6:7]
	v_mov_b64_e32 v[36:37], v[4:5]
	s_waitcnt vmcnt(0)
	v_mov_b32_e32 v51, v3

; template <class Map>
; DI void p0_transpose(const float* W, int K, int N, bf16_t* WT, const float* gain, const Map map, LAS float* scr, int& base, int gw, int NGW, int lane) {
;     ...
;         const int kb = it / nblk, nb = it % nblk, k0 = 64 * kb, c = 32 * nb + (lane & 31);
;         const float* p = W + (size_t)(k0 + (lane >> 5)) * N + c;
; #pragma unroll
;         for (int i = 0; i < 32; ++i) dst[i] = (c < N) ? p[(size_t)(2 * i) * N] : 0.f;
.LBB0_355:
	s_waitcnt vmcnt(1)
	v_add_co_u32_e32 v4, vcc, 0x20000, v106
	s_waitcnt vmcnt(0)
	s_nop 0
	v_addc_co_u32_e32 v5, vcc, 0, v107, vcc
	v_add_co_u32_e32 v6, vcc, 0x22000, v106
	s_nop 1
	v_addc_co_u32_e32 v7, vcc, 0, v107, vcc
	v_mov_b32_e32 v52, v220
	v_mov_b32_e32 v3, v221
	s_waitcnt vmcnt(1)
	v_mov_b64_e32 v[4:5], v[36:37]
	v_mov_b64_e32 v[20:21], v[52:53]
	v_mov_b64_e32 v[6:7], v[38:39]
	v_mov_b64_e32 v[8:9], v[40:41]
	v_mov_b64_e32 v[10:11], v[42:43]
	v_mov_b64_e32 v[12:13], v[44:45]
	v_mov_b64_e32 v[14:15], v[46:47]
	v_mov_b64_e32 v[16:17], v[48:49]
	v_mov_b64_e32 v[18:19], v[50:51]
	v_mov_b64_e32 v[22:23], v[54:55]
	v_mov_b64_e32 v[24:25], v[56:57]
	v_mov_b64_e32 v[26:27], v[58:59]
	v_mov_b64_e32 v[28:29], v[60:61]
	v_mov_b64_e32 v[30:31], v[62:63]
	v_mov_b64_e32 v[32:33], v[64:65]
	v_mov_b64_e32 v[34:35], v[66:67]
	s_waitcnt vmcnt(0)
	v_mov_b32_e32 v21, v3

; template <class Map>
; DI void p0_transpose(const float* W, int K, int N, bf16_t* WT, const float* gain, const Map map, LAS float* scr, int& base, int gw, int NGW, int lane) {
;     ...
;         const int kb = it / nblk, nb = it % nblk, k0 = 64 * kb, c = 32 * nb + (lane & 31);
;         const float* p = W + (size_t)(k0 + (lane >> 5)) * N + c;
; #pragma unroll
;         for (int i = 0; i < 32; ++i) dst[i] = (c < N) ? p[(size_t)(2 * i) * N] : 0.f;
.LBB0_359:
	v_add_co_u32_e32 v36, vcc, 0x24000, v106
	s_nop 1
	v_addc_co_u32_e32 v37, vcc, 0, v107, vcc
	v_add_co_u32_e32 v38, vcc, 0x26000, v106
	s_nop 1
	v_addc_co_u32_e32 v39, vcc, 0, v107, vcc
	v_mov_b32_e32 v22, v222
	v_mov_b32_e32 v3, v223
	s_waitcnt vmcnt(1)
	v_mov_b64_e32 v[66:67], v[34:35]
	v_mov_b64_e32 v[54:55], v[22:23]
	v_mov_b64_e32 v[64:65], v[32:33]
	v_mov_b64_e32 v[62:63], v[30:31]
	v_mov_b64_e32 v[60:61], v[28:29]
	v_mov_b64_e32 v[58:59], v[26:27]
	v_mov_b64_e32 v[56:57], v[24:25]
	v_mov_b64_e32 v[52:53], v[20:21]
	v_mov_b64_e32 v[50:51], v[18:19]
	v_mov_b64_e32 v[48:49], v[16:17]
	v_mov_b64_e32 v[46:47], v[14:15]
	v_mov_b64_e32 v[44:45], v[12:13]
	v_mov_b64_e32 v[42:43], v[10:11]
	v_mov_b64_e32 v[40:41], v[8:9]
	v_mov_b64_e32 v[38:39], v[6:7]
	v_mov_b64_e32 v[36:37], v[4:5]
	s_waitcnt vmcnt(0)
	v_mov_b32_e32 v55, v3

; template <class Map>
; DI void p0_transpose(const float* W, int K, int N, bf16_t* WT, const float* gain, const Map map, LAS float* scr, int& base, int gw, int NGW, int lane) {
;     ...
;         const int kb = it / nblk, nb = it % nblk, k0 = 64 * kb, c = 32 * nb + (lane & 31);
;         const float* p = W + (size_t)(k0 + (lane >> 5)) * N + c;
; #pragma unroll
;         for (int i = 0; i < 32; ++i) dst[i] = (c < N) ? p[(size_t)(2 * i) * N] : 0.f;
.LBB0_363:
	s_waitcnt vmcnt(1)
	v_add_co_u32_e32 v4, vcc, 0x28000, v106
	s_waitcnt vmcnt(0)
	s_nop 0
	v_addc_co_u32_e32 v5, vcc, 0, v107, vcc
	v_add_co_u32_e32 v6, vcc, 0x2a000, v106
	s_nop 1
	v_addc_co_u32_e32 v7, vcc, 0, v107, vcc
	v_mov_b32_e32 v56, v224
	v_mov_b32_e32 v3, v225
	s_waitcnt vmcnt(1)
	v_mov_b64_e32 v[4:5], v[36:37]
	v_mov_b64_e32 v[24:25], v[56:57]
	v_mov_b64_e32 v[6:7], v[38:39]
	v_mov_b64_e32 v[8:9], v[40:41]
	v_mov_b64_e32 v[10:11], v[42:43]
	v_mov_b64_e32 v[12:13], v[44:45]
	v_mov_b64_e32 v[14:15], v[46:47]
	v_mov_b64_e32 v[16:17], v[48:49]
	v_mov_b64_e32 v[18:19], v[50:51]
	v_mov_b64_e32 v[20:21], v[52:53]
	v_mov_b64_e32 v[22:23], v[54:55]
	v_mov_b64_e32 v[26:27], v[58:59]
	v_mov_b64_e32 v[28:29], v[60:61]
	v_mov_b64_e32 v[30:31], v[62:63]
	v_mov_b64_e32 v[32:33], v[64:65]
	v_mov_b64_e32 v[34:35], v[66:67]
	s_waitcnt vmcnt(0)
	v_mov_b32_e32 v25, v3

; template <class Map>
; DI void p0_transpose(const float* W, int K, int N, bf16_t* WT, const float* gain, const Map map, LAS float* scr, int& base, int gw, int NGW, int lane) {
;     ...
;         const int kb = it / nblk, nb = it % nblk, k0 = 64 * kb, c = 32 * nb + (lane & 31);
;         const float* p = W + (size_t)(k0 + (lane >> 5)) * N + c;
; #pragma unroll
;         for (int i = 0; i < 32; ++i) dst[i] = (c < N) ? p[(size_t)(2 * i) * N] : 0.f;
.LBB0_367:
	v_add_co_u32_e32 v36, vcc, 0x2c000, v106
	s_nop 1
	v_addc_co_u32_e32 v37, vcc, 0, v107, vcc
	v_add_co_u32_e32 v38, vcc, 0x2e000, v106
	s_nop 1
	v_addc_co_u32_e32 v39, vcc, 0, v107, vcc
	v_mov_b32_e32 v26, v226
	v_mov_b32_e32 v3, v227
	s_waitcnt vmcnt(1)
	v_mov_b64_e32 v[66:67], v[34:35]
	v_mov_b64_e32 v[58:59], v[26:27]
	v_mov_b64_e32 v[64:65], v[32:33]
	v_mov_b64_e32 v[62:63], v[30:31]
	v_mov_b64_e32 v[60:61], v[28:29]
	v_mov_b64_e32 v[56:57], v[24:25]
	v_mov_b64_e32 v[54:55], v[22:23]
	v_mov_b64_e32 v[52:53], v[20:21]
	v_mov_b64_e32 v[50:51], v[18:19]
	v_mov_b64_e32 v[48:49], v[16:17]
	v_mov_b64_e32 v[46:47], v[14:15]
	v_mov_b64_e32 v[44:45], v[12:13]
	v_mov_b64_e32 v[42:43], v[10:11]
	v_mov_b64_e32 v[40:41], v[8:9]
	v_mov_b64_e32 v[38:39], v[6:7]
	v_mov_b64_e32 v[36:37], v[4:5]
	s_waitcnt vmcnt(0)
	v_mov_b32_e32 v59, v3

; template <class Map>
; DI void p0_transpose(const float* W, int K, int N, bf16_t* WT, const float* gain, const Map map, LAS float* scr, int& base, int gw, int NGW, int lane) {
;     ...
;         const int kb = it / nblk, nb = it % nblk, k0 = 64 * kb, c = 32 * nb + (lane & 31);
;         const float* p = W + (size_t)(k0 + (lane >> 5)) * N + c;
; #pragma unroll
;         for (int i = 0; i < 32; ++i) dst[i] = (c < N) ? p[(size_t)(2 * i) * N] : 0.f;
.LBB0_371:
	s_waitcnt vmcnt(1)
	v_add_co_u32_e32 v4, vcc, 0x30000, v106
	s_waitcnt vmcnt(0)
	s_nop 0
	v_addc_co_u32_e32 v5, vcc, 0, v107, vcc
	v_add_co_u32_e32 v6, vcc, 0x32000, v106
	s_nop 1
	v_addc_co_u32_e32 v7, vcc, 0, v107, vcc
	v_mov_b32_e32 v60, v228
	v_mov_b32_e32 v3, v229
	s_waitcnt vmcnt(1)
	v_mov_b64_e32 v[4:5], v[36:37]
	v_mov_b64_e32 v[28:29], v[60:61]
	v_mov_b64_e32 v[6:7], v[38:39]
	v_mov_b64_e32 v[8:9], v[40:41]
	v_mov_b64_e32 v[10:11], v[42:43]
	v_mov_b64_e32 v[12:13], v[44:45]
	v_mov_b64_e32 v[14:15], v[46:47]
	v_mov_b64_e32 v[16:17], v[48:49]
	v_mov_b64_e32 v[18:19], v[50:51]
	v_mov_b64_e32 v[20:21], v[52:53]
	v_mov_b64_e32 v[22:23], v[54:55]
	v_mov_b64_e32 v[24:25], v[56:57]
	v_mov_b64_e32 v[26:27], v[58:59]
	v_mov_b64_e32 v[30:31], v[62:63]
	v_mov_b64_e32 v[32:33], v[64:65]
	v_mov_b64_e32 v[34:35], v[66:67]
	s_waitcnt vmcnt(0)
	v_mov_b32_e32 v29, v3

; template <class Map>
; DI void p0_transpose(const float* W, int K, int N, bf16_t* WT, const float* gain, const Map map, LAS float* scr, int& base, int gw, int NGW, int lane) {
;     ...
;         const int kb = it / nblk, nb = it % nblk, k0 = 64 * kb, c = 32 * nb + (lane & 31);
;         const float* p = W + (size_t)(k0 + (lane >> 5)) * N + c;
; #pragma unroll
;         for (int i = 0; i < 32; ++i) dst[i] = (c < N) ? p[(size_t)(2 * i) * N] : 0.f;
.LBB0_375:
	v_add_co_u32_e32 v36, vcc, 0x34000, v106
	s_nop 1
	v_addc_co_u32_e32 v37, vcc, 0, v107, vcc
	v_add_co_u32_e32 v38, vcc, 0x36000, v106
	s_nop 1
	v_addc_co_u32_e32 v39, vcc, 0, v107, vcc
	v_mov_b32_e32 v30, v230
	v_mov_b32_e32 v3, v231
	s_waitcnt vmcnt(1)
	v_mov_b64_e32 v[98:99], v[34:35]
	v_mov_b64_e32 v[94:95], v[30:31]
	v_mov_b64_e32 v[96:97], v[32:33]
	v_mov_b64_e32 v[92:93], v[28:29]
	v_mov_b64_e32 v[90:91], v[26:27]
	v_mov_b64_e32 v[88:89], v[24:25]
	v_mov_b64_e32 v[86:87], v[22:23]
	v_mov_b64_e32 v[84:85], v[20:21]
	v_mov_b64_e32 v[82:83], v[18:19]
	v_mov_b64_e32 v[80:81], v[16:17]
	v_mov_b64_e32 v[78:79], v[14:15]
	v_mov_b64_e32 v[76:77], v[12:13]
	v_mov_b64_e32 v[74:75], v[10:11]
	v_mov_b64_e32 v[72:73], v[8:9]
	v_mov_b64_e32 v[70:71], v[6:7]
	v_mov_b64_e32 v[68:69], v[4:5]
	s_waitcnt vmcnt(0)
	v_mov_b32_e32 v95, v3

; template <class Map>
; DI void p0_transpose(const float* W, int K, int N, bf16_t* WT, const float* gain, const Map map, LAS float* scr, int& base, int gw, int NGW, int lane) {
;     ...
;         const int kb = it / nblk, nb = it % nblk, k0 = 64 * kb, c = 32 * nb + (lane & 31);
;         const float* p = W + (size_t)(k0 + (lane >> 5)) * N + c;
; #pragma unroll
;         for (int i = 0; i < 32; ++i) dst[i] = (c < N) ? p[(size_t)(2 * i) * N] : 0.f;
.LBB0_379:
	s_waitcnt vmcnt(1)
	v_add_co_u32_e32 v4, vcc, 0x38000, v106
	s_waitcnt vmcnt(0)
	s_nop 0
	v_addc_co_u32_e32 v5, vcc, 0, v107, vcc
	v_add_co_u32_e32 v6, vcc, 0x3a000, v106
	s_nop 1
	v_addc_co_u32_e32 v7, vcc, 0, v107, vcc
	v_mov_b32_e32 v96, v232
	v_mov_b32_e32 v3, v233
	s_waitcnt vmcnt(1)
	v_mov_b64_e32 v[36:37], v[68:69]
	v_mov_b64_e32 v[64:65], v[96:97]
	v_mov_b64_e32 v[38:39], v[70:71]
	v_mov_b64_e32 v[40:41], v[72:73]
	v_mov_b64_e32 v[42:43], v[74:75]
	v_mov_b64_e32 v[44:45], v[76:77]
	v_mov_b64_e32 v[46:47], v[78:79]
	v_mov_b64_e32 v[48:49], v[80:81]
	v_mov_b64_e32 v[50:51], v[82:83]
	v_mov_b64_e32 v[52:53], v[84:85]
	v_mov_b64_e32 v[54:55], v[86:87]
	v_mov_b64_e32 v[56:57], v[88:89]
	v_mov_b64_e32 v[58:59], v[90:91]
	v_mov_b64_e32 v[60:61], v[92:93]
	v_mov_b64_e32 v[62:63], v[94:95]
	v_mov_b64_e32 v[66:67], v[98:99]
	s_waitcnt vmcnt(0)
	v_mov_b32_e32 v65, v3

; template <class Map>
; DI void p0_transpose(const float* W, int K, int N, bf16_t* WT, const float* gain, const Map map, LAS float* scr, int& base, int gw, int NGW, int lane) {
;     ...
;         const int kb = it / nblk, nb = it % nblk, k0 = 64 * kb, c = 32 * nb + (lane & 31);
;         const float* p = W + (size_t)(k0 + (lane >> 5)) * N + c;
; #pragma unroll
;         for (int i = 0; i < 32; ++i) dst[i] = (c < N) ? p[(size_t)(2 * i) * N] : 0.f;
.LBB0_383:
	s_waitcnt vmcnt(1)
	v_add_co_u32_e32 v4, vcc, 0x3c000, v106
	s_waitcnt vmcnt(0)
	s_nop 0
	v_addc_co_u32_e32 v5, vcc, 0, v107, vcc
	v_add_co_u32_e32 v6, vcc, 0x3e000, v106
	s_nop 1
	v_addc_co_u32_e32 v7, vcc, 0, v107, vcc
	v_mov_b32_e32 v66, v234
	v_mov_b32_e32 v3, v235
	s_waitcnt vmcnt(1)
	v_mov_b64_e32 v[4:5], v[36:37]
	v_mov_b64_e32 v[34:35], v[66:67]
	v_mov_b64_e32 v[6:7], v[38:39]
	v_mov_b64_e32 v[8:9], v[40:41]
	v_mov_b64_e32 v[10:11], v[42:43]
	v_mov_b64_e32 v[12:13], v[44:45]
	v_mov_b64_e32 v[14:15], v[46:47]
	v_mov_b64_e32 v[16:17], v[48:49]
	v_mov_b64_e32 v[18:19], v[50:51]
	v_mov_b64_e32 v[20:21], v[52:53]
	v_mov_b64_e32 v[22:23], v[54:55]
	v_mov_b64_e32 v[24:25], v[56:57]
	v_mov_b64_e32 v[26:27], v[58:59]
	v_mov_b64_e32 v[28:29], v[60:61]
	v_mov_b64_e32 v[30:31], v[62:63]
	v_mov_b64_e32 v[32:33], v[64:65]
	s_waitcnt vmcnt(0)
	v_mov_b32_e32 v35, v3
